# plus chunk-prep step 2 (K K^T and decayed K Q^T fragments) re-emitted branch-free with the K fragments read once and all LDS reads issued up front (main prep loop)
# speedup vs baseline: 1.0202x; 1.0033x over previous
; #define LAS __attribute__((address_space(3)))
; #define MFMA16(a, b, c) __builtin_amdgcn_mfma_f32_16x16x32_bf16(a, b, c, 0, 0, 0)
; __device__ __forceinline__ void gdn_prep_item(LAS unsigned char* lds, int item, int b0, PrepRaw& R, int next_item, const bf16_t* qkv, const float* bg, const float* gconv_w, unsigned char* rec, float* gtarr) {
;     ...
;     {
;         const f32x4 z4 = (f32x4){0.f, 0.f, 0.f, 0.f};
;         {
;             const int ta = wave >> 1;
; #pragma unroll
;             for (int q = 0; q < 2; ++q) { const int tb = 2 * (wave & 1) + q; f32x4 acc = z4;
; #pragma unroll
;                 for (int s = 0; s < 4; ++s) { const bf16x8 af = *(const LAS bf16x8*)(lds + P2_KN + ((16 * ta + l15) * 136 + 32 * s + 8 * g) * 2), bfr = *(const LAS bf16x8*)(lds + P2_KN + ((16 * tb + l15) * 136 + 32 * s + 8 * g) * 2);
;                     acc = MFMA16(af, bfr, acc); }
;                 const int j = 16 * tb + l15; const float Gj = Gs[j];
; #pragma unroll
;                 for (int r = 0; r < 4; ++r) { const int i = 16 * ta + 4 * g + r; Lf[i * LS + j] = (i > j) ? Bs[i] * acc[r] * __expf(Gs[i] - Gj) : 0.f; } }
;         }
;         {
;             const int rt = wave >> 1, s = wave & 1; f32x4 a0 = z4, a1 = z4;
; #pragma unroll
;             for (int ks = 0; ks < 4; ++ks) { const bf16x8 qf = *(const LAS bf16x8*)(lds + P2_QN + ((16 * rt + l15) * 136 + 32 * ks + 8 * g) * 2);
;                 const bf16x8 k0 = *(const LAS bf16x8*)(lds + P2_KN + ((32 * s + l15) * 136 + 32 * ks + 8 * g) * 2), k1 = *(const LAS bf16x8*)(lds + P2_KN + ((32 * s + 16 + l15) * 136 + 32 * ks + 8 * g) * 2);
;                 a0 = MFMA16(k0, qf, a0); a1 = MFMA16(k1, qf, a1); }
;             const int i = 16 * rt + l15; const float Gi = Gs[i];
; #pragma unroll
;             for (int r = 0; r < 4; ++r) { const int ia = 32 * s + 4 * g + r, ib = ia + 16;
;                 a0[r] = (i >= ia) ? a0[r] * __expf(Gi - Gs[ia]) : 0.f; a1[r] = (i >= ib) ? a1[r] * __expf(Gi - Gs[ib]) : 0.f; }
;             *(bf16x8*)(rec + REC_AM + ((rt * 2 + s) * 64 + lane) * 16) = pack8(a0, a1);
.LBB0_508:
	s_ashr_i32 s14, s30, 1
	s_lshl_b32 s1, s14, 4
	v_lshrrev_b32_e32 v51, 4, v118
	v_or_b32_e32 v37, s1, v114
	v_mul_lo_u32 v46, v37, s23
	v_lshlrev_b32_e32 v36, 3, v51
	v_add_lshl_u32 v46, v46, v36, 1
	v_add_u32_e32 v50, 0, v46
	s_waitcnt lgkmcnt(0)
	s_barrier
	s_and_b32 s20, s30, 1
	s_lshl_b32 s0, s20, 5
	v_or_b32_e32 v96, s0, v114
	v_lshl_or_b32 v97, v51, 2, s1
	v_lshl_or_b32 v104, v51, 2, s0
	v_lshlrev_b32_e32 v101, 2, v97
	v_add_u32_e32 v101, 0x1d000, v101
	v_lshlrev_b32_e32 v102, 2, v96
	v_add_u32_e32 v102, 0x1d000, v102
	v_lshlrev_b32_e32 v103, 2, v37
	v_add_u32_e32 v103, 0x1d000, v103
	v_sub_u32_e32 v99, v37, v104
	v_lshlrev_b32_e32 v104, 2, v104
	v_add_u32_e32 v104, 0x1d000, v104
	s_movk_i32 s0, 0x88
	v_mad_u32_u24 v105, v96, s0, v36
	v_lshlrev_b32_e32 v105, 1, v105
	ds_read_b128 v[200:203], v101
	ds_read_b128 v[204:207], v101 offset:256
	ds_read_b32 v216, v102
	ds_read_b32 v217, v102 offset:64
	ds_read_b32 v218, v103
	ds_read_b128 v[208:211], v104
	ds_read_b128 v[212:215], v104 offset:64
	ds_read_b128 v[136:139], v50 offset:17408
	ds_read_b128 v[152:155], v105 offset:17408
	ds_read_b128 v[168:171], v105 offset:21760
	ds_read_b128 v[184:187], v50
	ds_read_b128 v[140:143], v50 offset:17472
	ds_read_b128 v[156:159], v105 offset:17472
	ds_read_b128 v[172:175], v105 offset:21824
	ds_read_b128 v[188:191], v50 offset:64
	ds_read_b128 v[144:147], v50 offset:17536
	ds_read_b128 v[160:163], v105 offset:17536
	ds_read_b128 v[176:179], v105 offset:21888
	ds_read_b128 v[192:195], v50 offset:128
	ds_read_b128 v[148:151], v50 offset:17600
	ds_read_b128 v[164:167], v105 offset:17600
	ds_read_b128 v[180:183], v105 offset:21952
	ds_read_b128 v[196:199], v50 offset:192
	v_sub_u32_e32 v98, v97, v96
	s_movk_i32 s0, 0x110
	v_mad_u32_u24 v100, v97, s0, 0
	v_lshl_add_u32 v100, v96, 2, v100
	v_add_u32_e32 v100, 0x11800, v100
	s_waitcnt lgkmcnt(14)
	v_sub_f32_e32 v80, v200, v216
	v_sub_f32_e32 v81, v201, v216
	v_sub_f32_e32 v82, v202, v216
	v_sub_f32_e32 v83, v203, v216
	v_mul_f32_e32 v80, 0x3fb8aa3b, v80
	v_mul_f32_e32 v81, 0x3fb8aa3b, v81
	v_mul_f32_e32 v82, 0x3fb8aa3b, v82
	v_mul_f32_e32 v83, 0x3fb8aa3b, v83
	v_exp_f32_e32 v80, v80
	v_exp_f32_e32 v81, v81
	v_exp_f32_e32 v82, v82
	v_exp_f32_e32 v83, v83
	v_sub_f32_e32 v84, v200, v217
	v_sub_f32_e32 v85, v201, v217
	v_sub_f32_e32 v86, v202, v217
	v_sub_f32_e32 v87, v203, v217
	v_mul_f32_e32 v84, 0x3fb8aa3b, v84
	v_mul_f32_e32 v85, 0x3fb8aa3b, v85
	v_mul_f32_e32 v86, 0x3fb8aa3b, v86
	v_mul_f32_e32 v87, 0x3fb8aa3b, v87
	v_exp_f32_e32 v84, v84
	v_exp_f32_e32 v85, v85
	v_exp_f32_e32 v86, v86
	v_exp_f32_e32 v87, v87
	v_sub_f32_e32 v88, v218, v208
	v_sub_f32_e32 v89, v218, v209
	v_sub_f32_e32 v90, v218, v210
	v_sub_f32_e32 v91, v218, v211
	v_mul_f32_e32 v88, 0x3fb8aa3b, v88
	v_mul_f32_e32 v89, 0x3fb8aa3b, v89
	v_mul_f32_e32 v90, 0x3fb8aa3b, v90
	v_mul_f32_e32 v91, 0x3fb8aa3b, v91
	v_exp_f32_e32 v88, v88
	v_exp_f32_e32 v89, v89
	v_exp_f32_e32 v90, v90
	v_exp_f32_e32 v91, v91
	v_sub_f32_e32 v92, v218, v212
	v_sub_f32_e32 v93, v218, v213
	v_sub_f32_e32 v94, v218, v214
	v_sub_f32_e32 v95, v218, v215
	v_mul_f32_e32 v92, 0x3fb8aa3b, v92
	v_mul_f32_e32 v93, 0x3fb8aa3b, v93
	v_mul_f32_e32 v94, 0x3fb8aa3b, v94
	v_mul_f32_e32 v95, 0x3fb8aa3b, v95
	v_exp_f32_e32 v92, v92
	v_exp_f32_e32 v93, v93
	v_exp_f32_e32 v94, v94
	v_exp_f32_e32 v95, v95
	s_waitcnt lgkmcnt(12)
	v_mfma_f32_16x16x32_bf16 v[64:67], v[136:139], v[152:155], 0
	v_mfma_f32_16x16x32_bf16 v[68:71], v[136:139], v[168:171], 0
	v_mfma_f32_16x16x32_bf16 v[72:75], v[152:155], v[184:187], 0
	v_mfma_f32_16x16x32_bf16 v[76:79], v[168:171], v[184:187], 0
	s_waitcnt lgkmcnt(8)
	v_mfma_f32_16x16x32_bf16 v[64:67], v[140:143], v[156:159], v[64:67]
	v_mfma_f32_16x16x32_bf16 v[68:71], v[140:143], v[172:175], v[68:71]
	v_mfma_f32_16x16x32_bf16 v[72:75], v[156:159], v[188:191], v[72:75]
	v_mfma_f32_16x16x32_bf16 v[76:79], v[172:175], v[188:191], v[76:79]
	s_waitcnt lgkmcnt(4)
	v_mfma_f32_16x16x32_bf16 v[64:67], v[144:147], v[160:163], v[64:67]
	v_mfma_f32_16x16x32_bf16 v[68:71], v[144:147], v[176:179], v[68:71]
	v_mfma_f32_16x16x32_bf16 v[72:75], v[160:163], v[192:195], v[72:75]
	v_mfma_f32_16x16x32_bf16 v[76:79], v[176:179], v[192:195], v[76:79]
	s_waitcnt lgkmcnt(0)
	v_mfma_f32_16x16x32_bf16 v[64:67], v[148:151], v[164:167], v[64:67]
	v_mfma_f32_16x16x32_bf16 v[68:71], v[148:151], v[180:183], v[68:71]
	v_mfma_f32_16x16x32_bf16 v[72:75], v[164:167], v[196:199], v[72:75]
	v_mfma_f32_16x16x32_bf16 v[76:79], v[180:183], v[196:199], v[76:79]
	v_cmp_lt_i32_e64 s[36:37], 0, v98
	v_cmp_lt_i32_e64 s[38:39], -1, v98
	v_cmp_lt_i32_e64 s[40:41], -2, v98
	v_cmp_lt_i32_e64 s[42:43], -3, v98
	s_nop 3
	v_mul_f32_e32 v119, v64, v204
	v_mul_f32_e32 v120, v65, v205
	v_mul_f32_e32 v121, v66, v206
	v_mul_f32_e32 v122, v67, v207
	v_mul_f32_e32 v119, v119, v80
	v_mul_f32_e32 v120, v120, v81
	v_mul_f32_e32 v121, v121, v82
	v_mul_f32_e32 v122, v122, v83
	v_cndmask_b32_e64 v119, 0, v119, s[36:37]
	v_cndmask_b32_e64 v120, 0, v120, s[38:39]
	v_cndmask_b32_e64 v121, 0, v121, s[40:41]
	v_cndmask_b32_e64 v122, 0, v122, s[42:43]
	ds_write_b32 v100, v119
	ds_write_b32 v100, v120 offset:272
	ds_write_b32 v100, v121 offset:544
	ds_write_b32 v100, v122 offset:816
	v_cmp_lt_i32_e64 s[36:37], 16, v98
	v_cmp_lt_i32_e64 s[38:39], 15, v98
	v_cmp_lt_i32_e64 s[40:41], 14, v98
	v_cmp_lt_i32_e64 s[42:43], 13, v98
	v_mul_f32_e32 v119, v68, v204
	v_mul_f32_e32 v120, v69, v205
	v_mul_f32_e32 v121, v70, v206
	v_mul_f32_e32 v122, v71, v207
	v_mul_f32_e32 v119, v119, v84
	v_mul_f32_e32 v120, v120, v85
	v_mul_f32_e32 v121, v121, v86
	v_mul_f32_e32 v122, v122, v87
	v_cndmask_b32_e64 v119, 0, v119, s[36:37]
; #define LAS __attribute__((address_space(3)))
; __device__ __forceinline__ void gdn_prep_item(LAS unsigned char* lds, int item, int b0, PrepRaw& R, int next_item, const bf16_t* qkv, const float* bg, const float* gconv_w, unsigned char* rec, float* gtarr) {
;     ...
;             const int i = 16 * rt + l15; const float Gi = Gs[i];
; #pragma unroll
;             for (int r = 0; r < 4; ++r) { const int ia = 32 * s + 4 * g + r, ib = ia + 16;
;                 a0[r] = (i >= ia) ? a0[r] * __expf(Gi - Gs[ia]) : 0.f; a1[r] = (i >= ib) ? a1[r] * __expf(Gi - Gs[ib]) : 0.f; }
;             *(bf16x8*)(rec + REC_AM + ((rt * 2 + s) * 64 + lane) * 16) = pack8(a0, a1);
;         }
;     }
;     __syncthreads();
;     if (tid < 64) { const int blk = tid >> 4, cidx = tid & 15; float x[16];
; #pragma unroll
;         for (int i = 0; i < 16; ++i) x[i] = (i == cidx) ? 1.f : 0.f;
; #pragma unroll
;         for (int i = 1; i < 16; ++i) { float a = 0.f; const LAS float* row = Lf + (16 * blk + i) * LS + 16 * blk;
; #pragma unroll
;             for (int j4 = 0; j4 < (i + 3) / 4; ++j4) { const f32x4 l4 = *(const LAS f32x4*)(row + 4 * j4);
; #pragma unroll
;                 for (int e = 0; e < 4; ++e) if (4 * j4 + e < i) a += l4[e] * x[4 * j4 + e]; }
;             if (i > cidx) x[i] = -a; }
; #pragma unroll
;         for (int i = 0; i < 16; ++i) Tf[(16 * blk + i) * LS + 16 * blk + cidx] = x[i];
;     }
	v_cndmask_b32_e64 v120, 0, v120, s[38:39]
	v_cndmask_b32_e64 v121, 0, v121, s[40:41]
	v_cndmask_b32_e64 v122, 0, v122, s[42:43]
	ds_write_b32 v100, v119 offset:64
	ds_write_b32 v100, v120 offset:336
	ds_write_b32 v100, v121 offset:608
	ds_write_b32 v100, v122 offset:880
	v_cmp_le_i32_e64 s[36:37], 0, v99
	v_cmp_le_i32_e64 s[38:39], 1, v99
	v_cmp_le_i32_e64 s[40:41], 2, v99
	v_cmp_le_i32_e64 s[42:43], 3, v99
	v_mul_f32_e32 v72, v72, v88
	v_mul_f32_e32 v73, v73, v89
	v_mul_f32_e32 v74, v74, v90
	v_mul_f32_e32 v75, v75, v91
	v_cndmask_b32_e64 v72, 0, v72, s[36:37]
	v_cndmask_b32_e64 v73, 0, v73, s[38:39]
	v_cndmask_b32_e64 v74, 0, v74, s[40:41]
	v_cndmask_b32_e64 v75, 0, v75, s[42:43]
	v_cvt_pk_bf16_f32 v60, v72, v73
	v_cvt_pk_bf16_f32 v61, v74, v75
	v_cmp_le_i32_e64 s[36:37], 16, v99
	v_cmp_le_i32_e64 s[38:39], 17, v99
	v_cmp_le_i32_e64 s[40:41], 18, v99
	v_cmp_le_i32_e64 s[42:43], 19, v99
	v_mul_f32_e32 v76, v76, v92
	v_mul_f32_e32 v77, v77, v93
	v_mul_f32_e32 v78, v78, v94
	v_mul_f32_e32 v79, v79, v95
	v_cndmask_b32_e64 v76, 0, v76, s[36:37]
	v_cndmask_b32_e64 v77, 0, v77, s[38:39]
	v_cndmask_b32_e64 v78, 0, v78, s[40:41]
	v_cndmask_b32_e64 v79, 0, v79, s[42:43]
	v_cvt_pk_bf16_f32 v62, v76, v77
	v_cvt_pk_bf16_f32 v63, v78, v79
	s_add_i32 s0, s18, 0xfffff9c8
	s_cmpk_lt_i32 s18, 0x638
	s_cselect_b32 s0, s18, s0
	s_cselect_b32 s1, s19, 0
	v_readlane_b32 s36, v245, 19
	v_readlane_b32 s48, v245, 31
	v_readlane_b32 s49, v245, 32
	s_mul_i32 s1, s1, 0x12000
	s_mul_hi_u32 s6, s0, 0x12000
	s_cselect_b32 s5, s64, s49
	s_cselect_b32 s4, s33, s48
	s_add_i32 s6, s6, s1
	s_mul_i32 s0, s0, 0x12000
	v_lshlrev_b32_e32 v50, 4, v118
	s_add_u32 s4, s4, s0
	v_lshl_or_b32 v46, s30, 10, v50
	s_addc_u32 s5, s5, s6
	v_ashrrev_i32_e32 v47, 31, v46
	v_lshl_add_u64 v[46:47], s[4:5], 0, v[46:47]
	v_add_co_u32_e32 v46, vcc, 0xc000, v46
	s_nop 0
	v_addc_co_u32_e32 v47, vcc, 0, v47, vcc
	s_waitcnt lgkmcnt(0)
	v_cmp_gt_i32_e32 vcc, 64, v116
	v_readlane_b32 s37, v245, 20
	v_readlane_b32 s38, v245, 21
	v_readlane_b32 s39, v245, 22
	v_readlane_b32 s40, v245, 23
	v_readlane_b32 s41, v245, 24
	v_readlane_b32 s42, v245, 25
	v_readlane_b32 s43, v245, 26
	v_readlane_b32 s44, v245, 27
	v_readlane_b32 s45, v245, 28
	v_readlane_b32 s46, v245, 29
	v_readlane_b32 s47, v245, 30
	v_readlane_b32 s50, v245, 33
	v_readlane_b32 s51, v245, 34
	global_store_dwordx4 v[46:47], v[60:63], off
	s_barrier
	s_and_saveexec_b64 s[6:7], vcc
	s_cbranch_execz .LBB0_542
	v_and_b32_e32 v61, -16, v116
	v_lshlrev_b32_e32 v96, 8, v61
	v_lshl_add_u32 v96, v61, 4, v96
	v_lshl_add_u32 v96, v61, 2, v96
	v_add_u32_e32 v97, 0x11800, v96
	v_lshl_add_u32 v119, v114, 2, v96
	v_add_u32_e32 v119, 0x15c00, v119
	v_cmp_eq_u32_e32 vcc, 0, v114
	s_nop 1
	v_cndmask_b32_e64 v248, 0, 1.0, vcc
	ds_read_b128 v[136:139], v97 offset:272
	ds_read_b128 v[140:143], v97 offset:544
	ds_read_b128 v[144:147], v97 offset:816
	ds_read_b128 v[148:151], v97 offset:1088
	ds_read_b128 v[152:155], v97 offset:1360
	ds_read_b128 v[156:159], v97 offset:1376
	ds_read_b128 v[160:163], v97 offset:1632
	ds_read_b128 v[164:167], v97 offset:1648
	ds_read_b128 v[168:171], v97 offset:1904
	ds_read_b128 v[172:175], v97 offset:1920
	ds_read_b128 v[176:179], v97 offset:2176
	ds_read_b128 v[180:183], v97 offset:2192
	ds_read_b128 v[184:187], v97 offset:2448
	ds_read_b128 v[188:191], v97 offset:2464
	s_waitcnt lgkmcnt(13)
	v_cmp_eq_u32_e64 s[0:1], 1, v114
	v_cmp_gt_u32_e32 vcc, 1, v114
	v_fma_f32 v132, v248, v136, 0
	s_nop 1
	v_cndmask_b32_e64 v249, 0, 1.0, s[0:1]
	v_cndmask_b32_e64 v249, v249, -v132, vcc
	ds_read_b128 v[192:195], v97 offset:2480
	s_waitcnt lgkmcnt(13)
	v_cmp_eq_u32_e64 s[0:1], 2, v114
	v_cmp_gt_u32_e32 vcc, 2, v114
	v_fma_f32 v133, v248, v140, 0
	v_fmac_f32_e32 v133, v141, v249
	s_nop 1
	v_cndmask_b32_e64 v250, 0, 1.0, s[0:1]
	v_cndmask_b32_e64 v250, v250, -v133, vcc
	ds_read_b128 v[196:199], v97 offset:2720
	s_waitcnt lgkmcnt(13)
	v_cmp_eq_u32_e64 s[0:1], 3, v114
	v_cmp_gt_u32_e32 vcc, 3, v114
	v_fma_f32 v132, v248, v144, 0
	v_fmac_f32_e32 v132, v145, v249
	v_fmac_f32_e32 v132, v146, v250
	v_cndmask_b32_e64 v251, 0, 1.0, s[0:1]
	v_cndmask_b32_e64 v251, v251, -v132, vcc
	ds_read_b128 v[200:203], v97 offset:2736
	s_waitcnt lgkmcnt(13)
	v_cmp_eq_u32_e64 s[0:1], 4, v114
	v_cmp_gt_u32_e32 vcc, 4, v114
	v_fma_f32 v133, v248, v148, 0
	v_fmac_f32_e32 v133, v149, v249
	v_fmac_f32_e32 v133, v150, v250
	v_fmac_f32_e32 v133, v151, v251
	v_cndmask_b32_e64 v252, 0, 1.0, s[0:1]
	v_cndmask_b32_e64 v252, v252, -v133, vcc
	ds_read_b128 v[204:207], v97 offset:2752
	s_waitcnt lgkmcnt(13)
	v_cmp_eq_u32_e64 s[0:1], 5, v114
	v_cmp_gt_u32_e32 vcc, 5, v114
	v_fma_f32 v132, v248, v152, 0
	v_fmac_f32_e32 v132, v153, v249
	v_fmac_f32_e32 v132, v154, v250
	v_fmac_f32_e32 v132, v155, v251
	ds_read_b128 v[208:211], v97 offset:2992
	s_waitcnt lgkmcnt(13)
	v_fmac_f32_e32 v132, v156, v252
	v_cndmask_b32_e64 v253, 0, 1.0, s[0:1]
	v_cndmask_b32_e64 v253, v253, -v132, vcc
	ds_read_b128 v[212:215], v97 offset:3008
	s_waitcnt lgkmcnt(13)
	v_cmp_eq_u32_e64 s[0:1], 6, v114
	v_cmp_gt_u32_e32 vcc, 6, v114
	v_fma_f32 v133, v248, v160, 0
	v_fmac_f32_e32 v133, v161, v249
	v_fmac_f32_e32 v133, v162, v250
	v_fmac_f32_e32 v133, v163, v251
	ds_read_b128 v[216:219], v97 offset:3024
	s_waitcnt lgkmcnt(13)
	v_fmac_f32_e32 v133, v164, v252
	v_fmac_f32_e32 v133, v165, v253
	v_cndmask_b32_e64 v254, 0, 1.0, s[0:1]
	v_cndmask_b32_e64 v254, v254, -v133, vcc
	ds_read_b128 v[64:67], v97 offset:3264
	s_waitcnt lgkmcnt(13)
	v_cmp_eq_u32_e64 s[0:1], 7, v114
	v_cmp_gt_u32_e32 vcc, 7, v114
	v_fma_f32 v132, v248, v168, 0
	v_fmac_f32_e32 v132, v169, v249
	v_fmac_f32_e32 v132, v170, v250
	v_fmac_f32_e32 v132, v171, v251
	ds_read_b128 v[68:71], v97 offset:3280
	s_waitcnt lgkmcnt(13)
; #define LAS __attribute__((address_space(3)))
; __device__ __forceinline__ void gdn_prep_item(LAS unsigned char* lds, int item, int b0, PrepRaw& R, int next_item, const bf16_t* qkv, const float* bg, const float* gconv_w, unsigned char* rec, float* gtarr) {
;     ...
;     if (tid < 64) { const int blk = tid >> 4, cidx = tid & 15; float x[16];
; #pragma unroll
;         for (int i = 0; i < 16; ++i) x[i] = (i == cidx) ? 1.f : 0.f;
; #pragma unroll
;         for (int i = 1; i < 16; ++i) { float a = 0.f; const LAS float* row = Lf + (16 * blk + i) * LS + 16 * blk;
; #pragma unroll
;             for (int j4 = 0; j4 < (i + 3) / 4; ++j4) { const f32x4 l4 = *(const LAS f32x4*)(row + 4 * j4);
; #pragma unroll
;                 for (int e = 0; e < 4; ++e) if (4 * j4 + e < i) a += l4[e] * x[4 * j4 + e]; }
;             if (i > cidx) x[i] = -a; }
; #pragma unroll
;         for (int i = 0; i < 16; ++i) Tf[(16 * blk + i) * LS + 16 * blk + cidx] = x[i];
;     }
	v_fmac_f32_e32 v132, v172, v252
	v_fmac_f32_e32 v132, v173, v253
	v_fmac_f32_e32 v132, v174, v254
	v_cndmask_b32_e64 v255, 0, 1.0, s[0:1]
	v_cndmask_b32_e64 v255, v255, -v132, vcc
	ds_read_b128 v[72:75], v97 offset:3296
	s_waitcnt lgkmcnt(13)
	v_cmp_eq_u32_e64 s[0:1], 8, v114
	v_cmp_gt_u32_e32 vcc, 8, v114
	v_fma_f32 v133, v248, v176, 0
	v_fmac_f32_e32 v133, v177, v249
	v_fmac_f32_e32 v133, v178, v250
	v_fmac_f32_e32 v133, v179, v251
	ds_read_b128 v[76:79], v97 offset:3536
	s_waitcnt lgkmcnt(13)
	v_fmac_f32_e32 v133, v180, v252
	v_fmac_f32_e32 v133, v181, v253
	v_fmac_f32_e32 v133, v182, v254
	v_fmac_f32_e32 v133, v183, v255
	v_cndmask_b32_e64 v240, 0, 1.0, s[0:1]
	v_cndmask_b32_e64 v240, v240, -v133, vcc
	ds_read_b128 v[80:83], v97 offset:3552
	s_waitcnt lgkmcnt(13)
	v_cmp_eq_u32_e64 s[0:1], 9, v114
	v_cmp_gt_u32_e32 vcc, 9, v114
	v_fma_f32 v132, v248, v184, 0
	v_fmac_f32_e32 v132, v185, v249
	v_fmac_f32_e32 v132, v186, v250
	v_fmac_f32_e32 v132, v187, v251
	ds_read_b128 v[84:87], v97 offset:3568
	s_waitcnt lgkmcnt(13)
	v_fmac_f32_e32 v132, v188, v252
	v_fmac_f32_e32 v132, v189, v253
	v_fmac_f32_e32 v132, v190, v254
	v_fmac_f32_e32 v132, v191, v255
	ds_read_b128 v[88:91], v97 offset:3584
	s_waitcnt lgkmcnt(13)
	v_fmac_f32_e32 v132, v192, v240
	v_cndmask_b32_e64 v241, 0, 1.0, s[0:1]
	v_cndmask_b32_e64 v241, v241, -v132, vcc
	ds_read_b128 v[92:95], v97 offset:3808
	s_waitcnt lgkmcnt(13)
	v_cmp_eq_u32_e64 s[0:1], 10, v114
	v_cmp_gt_u32_e32 vcc, 10, v114
	v_fma_f32 v133, v248, v196, 0
	v_fmac_f32_e32 v133, v197, v249
	v_fmac_f32_e32 v133, v198, v250
	v_fmac_f32_e32 v133, v199, v251
	ds_read_b128 v[120:123], v97 offset:3824
	s_waitcnt lgkmcnt(13)
	v_fmac_f32_e32 v133, v200, v252
	v_fmac_f32_e32 v133, v201, v253
	v_fmac_f32_e32 v133, v202, v254
	v_fmac_f32_e32 v133, v203, v255
	ds_read_b128 v[124:127], v97 offset:3840
	s_waitcnt lgkmcnt(13)
	v_fmac_f32_e32 v133, v204, v240
	v_fmac_f32_e32 v133, v205, v241
	v_cndmask_b32_e64 v242, 0, 1.0, s[0:1]
	v_cndmask_b32_e64 v242, v242, -v133, vcc
	ds_read_b128 v[128:131], v97 offset:3856
	s_waitcnt lgkmcnt(13)
	v_cmp_eq_u32_e64 s[0:1], 11, v114
	v_cmp_gt_u32_e32 vcc, 11, v114
	v_fma_f32 v132, v248, v208, 0
	v_fmac_f32_e32 v132, v209, v249
	v_fmac_f32_e32 v132, v210, v250
	v_fmac_f32_e32 v132, v211, v251
	ds_read_b128 v[222:225], v97 offset:4080
	s_waitcnt lgkmcnt(13)
	v_fmac_f32_e32 v132, v212, v252
	v_fmac_f32_e32 v132, v213, v253
	v_fmac_f32_e32 v132, v214, v254
	v_fmac_f32_e32 v132, v215, v255
	ds_read_b128 v[226:229], v97 offset:4096
	s_waitcnt lgkmcnt(13)
	v_fmac_f32_e32 v132, v216, v240
	v_fmac_f32_e32 v132, v217, v241
	v_fmac_f32_e32 v132, v218, v242
	v_cndmask_b32_e64 v243, 0, 1.0, s[0:1]
	v_cndmask_b32_e64 v243, v243, -v132, vcc
	ds_read_b128 v[230:233], v97 offset:4112
	s_waitcnt lgkmcnt(13)
	v_cmp_eq_u32_e64 s[0:1], 12, v114
	v_cmp_gt_u32_e32 vcc, 12, v114
	v_fma_f32 v133, v248, v64, 0
	v_fmac_f32_e32 v133, v65, v249
	v_fmac_f32_e32 v133, v66, v250
	v_fmac_f32_e32 v133, v67, v251
	ds_read_b128 v[234:237], v97 offset:4128
	s_waitcnt lgkmcnt(13)
	v_fmac_f32_e32 v133, v68, v252
	v_fmac_f32_e32 v133, v69, v253
	v_fmac_f32_e32 v133, v70, v254
	v_fmac_f32_e32 v133, v71, v255
	s_waitcnt lgkmcnt(12)
	v_fmac_f32_e32 v133, v72, v240
	v_fmac_f32_e32 v133, v73, v241
	v_fmac_f32_e32 v133, v74, v242
	v_fmac_f32_e32 v133, v75, v243
	v_cndmask_b32_e64 v102, 0, 1.0, s[0:1]
	v_cndmask_b32_e64 v102, v102, -v133, vcc
	s_waitcnt lgkmcnt(11)
	v_cmp_eq_u32_e64 s[0:1], 13, v114
	v_cmp_gt_u32_e32 vcc, 13, v114
	v_fma_f32 v132, v248, v76, 0
	v_fmac_f32_e32 v132, v77, v249
	v_fmac_f32_e32 v132, v78, v250
	v_fmac_f32_e32 v132, v79, v251
	s_waitcnt lgkmcnt(10)
	v_fmac_f32_e32 v132, v80, v252
	v_fmac_f32_e32 v132, v81, v253
	v_fmac_f32_e32 v132, v82, v254
	v_fmac_f32_e32 v132, v83, v255
	s_waitcnt lgkmcnt(9)
	v_fmac_f32_e32 v132, v84, v240
	v_fmac_f32_e32 v132, v85, v241
	v_fmac_f32_e32 v132, v86, v242
	v_fmac_f32_e32 v132, v87, v243
	s_waitcnt lgkmcnt(8)
	v_fmac_f32_e32 v132, v88, v102
	v_cndmask_b32_e64 v103, 0, 1.0, s[0:1]
	v_cndmask_b32_e64 v103, v103, -v132, vcc
	s_waitcnt lgkmcnt(7)
	v_cmp_eq_u32_e64 s[0:1], 14, v114
	v_cmp_gt_u32_e32 vcc, 14, v114
	v_fma_f32 v133, v248, v92, 0
	v_fmac_f32_e32 v133, v93, v249
	v_fmac_f32_e32 v133, v94, v250
	v_fmac_f32_e32 v133, v95, v251
	s_waitcnt lgkmcnt(6)
	v_fmac_f32_e32 v133, v120, v252
	v_fmac_f32_e32 v133, v121, v253
	v_fmac_f32_e32 v133, v122, v254
	v_fmac_f32_e32 v133, v123, v255
	s_waitcnt lgkmcnt(5)
	v_fmac_f32_e32 v133, v124, v240
	v_fmac_f32_e32 v133, v125, v241
	v_fmac_f32_e32 v133, v126, v242
	v_fmac_f32_e32 v133, v127, v243
	s_waitcnt lgkmcnt(4)
	v_fmac_f32_e32 v133, v128, v102
	v_fmac_f32_e32 v133, v129, v103
	v_cndmask_b32_e64 v104, 0, 1.0, s[0:1]
	v_cndmask_b32_e64 v104, v104, -v133, vcc
	s_waitcnt lgkmcnt(3)
	v_cmp_eq_u32_e64 s[0:1], 15, v114
	v_cmp_gt_u32_e32 vcc, 15, v114
	v_fma_f32 v132, v248, v222, 0
	v_fmac_f32_e32 v132, v223, v249
	v_fmac_f32_e32 v132, v224, v250
	v_fmac_f32_e32 v132, v225, v251
	s_waitcnt lgkmcnt(2)
	v_fmac_f32_e32 v132, v226, v252
	v_fmac_f32_e32 v132, v227, v253
	v_fmac_f32_e32 v132, v228, v254
	v_fmac_f32_e32 v132, v229, v255
	s_waitcnt lgkmcnt(1)
	v_fmac_f32_e32 v132, v230, v240
	v_fmac_f32_e32 v132, v231, v241
	v_fmac_f32_e32 v132, v232, v242
	v_fmac_f32_e32 v132, v233, v243
	s_waitcnt lgkmcnt(0)
	v_fmac_f32_e32 v132, v234, v102
	v_fmac_f32_e32 v132, v235, v103
	v_fmac_f32_e32 v132, v236, v104
	v_cndmask_b32_e64 v105, 0, 1.0, s[0:1]
	v_cndmask_b32_e64 v105, v105, -v132, vcc
	ds_write_b32 v119, v248
	ds_write_b32 v119, v249 offset:272
	ds_write_b32 v119, v250 offset:544
	ds_write_b32 v119, v251 offset:816
	ds_write_b32 v119, v252 offset:1088
	ds_write_b32 v119, v253 offset:1360
	ds_write_b32 v119, v254 offset:1632
	ds_write_b32 v119, v255 offset:1904
	ds_write_b32 v119, v240 offset:2176
	ds_write_b32 v119, v241 offset:2448
	ds_write_b32 v119, v242 offset:2720
	ds_write_b32 v119, v243 offset:2992
	ds_write_b32 v119, v102 offset:3264
	ds_write_b32 v119, v103 offset:3536
	ds_write_b32 v119, v104 offset:3808
	ds_write_b32 v119, v105 offset:4080
